# diff_row phase: the second 4-head step's loads issued with the first step's at the row top (one memory round trip per row)
# speedup vs baseline: 1.0069x; 1.0020x over previous
.LBB0_28:
	global_load_dwordx4 v[20:23], v[12:13], off offset:-2048
	global_load_dwordx4 v[24:27], v[12:13], off offset:-1792
	global_load_dwordx4 v[48:51], v[12:13], off
	global_load_dwordx4 v[52:55], v[12:13], off offset:256
	s_add_i32 s6, s6, s8
	s_cmp_gt_i32 s6, 0x87ff
	s_waitcnt vmcnt(3)
	v_lshlrev_b32_e32 v14, 16, v23
	v_and_b32_e32 v15, 0xffff0000, v23
	s_waitcnt vmcnt(2)
	v_lshlrev_b32_e32 v28, 16, v27
	v_and_b32_e32 v29, 0xffff0000, v27
	v_pk_fma_f32 v[14:15], v[8:9], v[28:29], v[14:15] neg_lo:[1,0,0] neg_hi:[1,0,0]
	v_lshlrev_b32_e32 v28, 16, v22
	v_and_b32_e32 v29, 0xffff0000, v22
	v_lshlrev_b32_e32 v22, 16, v26
	v_and_b32_e32 v23, 0xffff0000, v26
	v_pk_fma_f32 v[22:23], v[8:9], v[22:23], v[28:29] neg_lo:[1,0,0] neg_hi:[1,0,0]
	v_mov_b32_e32 v26, v14
	v_mov_b32_e32 v27, v22
	v_pk_mul_f32 v[26:27], v[26:27], v[26:27]
	v_mov_b32_e32 v28, v15
	v_mov_b32_e32 v29, v23
	v_pk_fma_f32 v[26:27], v[28:29], v[28:29], v[26:27]
	v_lshlrev_b32_e32 v28, 16, v21
	v_and_b32_e32 v29, 0xffff0000, v21
	v_lshlrev_b32_e32 v30, 16, v25
	v_and_b32_e32 v31, 0xffff0000, v25
	v_lshlrev_b32_e32 v32, 16, v20
	v_and_b32_e32 v33, 0xffff0000, v20
	v_lshlrev_b32_e32 v20, 16, v24
	v_and_b32_e32 v21, 0xffff0000, v24
	v_pk_fma_f32 v[28:29], v[8:9], v[30:31], v[28:29] neg_lo:[1,0,0] neg_hi:[1,0,0]
	v_pk_fma_f32 v[20:21], v[8:9], v[20:21], v[32:33] neg_lo:[1,0,0] neg_hi:[1,0,0]
	v_pk_mul_f32 v[30:31], v[28:29], v[28:29]
	v_pk_mul_f32 v[24:25], v[20:21], v[20:21]
	v_add_f32_e32 v30, v31, v30
	v_add_f32_e32 v24, v25, v24
	v_add_f32_e32 v24, v24, v30
	v_add_f32_e32 v24, v27, v24
	v_add_f32_e32 v24, v26, v24
	ds_bpermute_b32 v25, v16, v24
	s_waitcnt lgkmcnt(0)
	v_add_f32_e32 v24, v24, v25
	ds_bpermute_b32 v25, v17, v24
	s_waitcnt lgkmcnt(0)
	v_add_f32_e32 v24, v24, v25
	ds_bpermute_b32 v25, v18, v24
	s_waitcnt lgkmcnt(0)
	v_add_f32_e32 v24, v24, v25
	ds_bpermute_b32 v25, v19, v24
	s_waitcnt lgkmcnt(0)
	v_add_f32_e32 v24, v24, v25
	v_fmamk_f32 v24, v24, 0x3c000000, v193
	v_cmp_gt_f32_e32 vcc, s67, v24
	v_mul_f32_e32 v25, 0x4f800000, v24
	s_nop 0
	v_cndmask_b32_e32 v24, v24, v25, vcc
	v_sqrt_f32_e32 v25, v24
	s_nop 0
	v_add_u32_e32 v26, -1, v25
	v_fma_f32 v27, -v26, v25, v24
	v_cmp_ge_f32_e64 s[2:3], 0, v27
	v_add_u32_e32 v27, 1, v25
	s_nop 0
	v_cndmask_b32_e64 v26, v25, v26, s[2:3]
	v_fma_f32 v25, -v27, v25, v24
	v_cmp_lt_f32_e64 s[2:3], 0, v25
	s_nop 1
	v_cndmask_b32_e64 v25, v26, v27, s[2:3]
	v_mul_f32_e32 v26, 0x37800000, v25
	v_cndmask_b32_e32 v25, v25, v26, vcc
	v_cmp_class_f32_e32 vcc, v24, v195
	s_nop 1
	v_cndmask_b32_e32 v24, v25, v24, vcc
	v_div_scale_f32 v25, s[2:3], v24, v24, 1.0
	v_rcp_f32_e32 v26, v25
	s_nop 0
	v_fma_f32 v27, -v25, v26, 1.0
	v_fmac_f32_e32 v26, v27, v26
	v_div_scale_f32 v27, vcc, 1.0, v24, 1.0
	v_mul_f32_e32 v30, v27, v26
	v_fma_f32 v31, -v25, v30, v27
	v_fmac_f32_e32 v30, v31, v26
	v_fma_f32 v25, -v25, v30, v27
	v_div_fmas_f32 v25, v25, v26, v30
	v_div_fixup_f32 v24, v25, v24, 1.0
	v_mul_f32_e32 v24, 0x3f24fd5c, v24
	v_pk_mul_f32 v[20:21], v[20:21], v[24:25] op_sel_hi:[1,0]
	v_pk_mul_f32 v[26:27], v[28:29], v[24:25] op_sel_hi:[1,0]
	v_pk_mul_f32 v[22:23], v[22:23], v[24:25] op_sel_hi:[1,0]
	v_pk_mul_f32 v[14:15], v[14:15], v[24:25] op_sel_hi:[1,0]
	v_pk_mul_f32 v[20:21], v[0:1], v[20:21]
	v_pk_mul_f32 v[26:27], v[2:3], v[26:27]
	v_pk_mul_f32 v[22:23], v[4:5], v[22:23]
	v_pk_mul_f32 v[14:15], v[6:7], v[14:15]
	v_cvt_pk_bf16_f32 v20, v20, v21
	v_cvt_pk_bf16_f32 v21, v26, v27
	v_cvt_pk_bf16_f32 v22, v22, v23
	v_cvt_pk_bf16_f32 v23, v14, v15
	global_store_dwordx4 v[10:11], v[20:23], off offset:-1024
	v_lshl_add_u64 v[12:13], v[12:13], 0, s[12:13]
	s_waitcnt vmcnt(2)
	v_lshlrev_b32_e32 v14, 16, v51
	v_and_b32_e32 v15, 0xffff0000, v51
	s_waitcnt vmcnt(1)
	v_lshlrev_b32_e32 v28, 16, v55
	v_and_b32_e32 v29, 0xffff0000, v55
	v_pk_fma_f32 v[14:15], v[8:9], v[28:29], v[14:15] neg_lo:[1,0,0] neg_hi:[1,0,0]
	v_lshlrev_b32_e32 v28, 16, v50
	v_and_b32_e32 v29, 0xffff0000, v50
	v_lshlrev_b32_e32 v22, 16, v54
	v_and_b32_e32 v23, 0xffff0000, v54
	v_pk_fma_f32 v[22:23], v[8:9], v[22:23], v[28:29] neg_lo:[1,0,0] neg_hi:[1,0,0]
	v_mov_b32_e32 v26, v14
	v_mov_b32_e32 v27, v22
	v_pk_mul_f32 v[26:27], v[26:27], v[26:27]
	v_mov_b32_e32 v28, v15
	v_mov_b32_e32 v29, v23
	v_pk_fma_f32 v[26:27], v[28:29], v[28:29], v[26:27]
	v_lshlrev_b32_e32 v28, 16, v49
	v_and_b32_e32 v29, 0xffff0000, v49
	v_lshlrev_b32_e32 v30, 16, v53
	v_and_b32_e32 v31, 0xffff0000, v53
	v_lshlrev_b32_e32 v32, 16, v48
	v_and_b32_e32 v33, 0xffff0000, v48
	v_lshlrev_b32_e32 v20, 16, v52
	v_and_b32_e32 v21, 0xffff0000, v52
	v_pk_fma_f32 v[28:29], v[8:9], v[30:31], v[28:29] neg_lo:[1,0,0] neg_hi:[1,0,0]
	v_pk_fma_f32 v[20:21], v[8:9], v[20:21], v[32:33] neg_lo:[1,0,0] neg_hi:[1,0,0]
	v_pk_mul_f32 v[30:31], v[28:29], v[28:29]
	v_pk_mul_f32 v[24:25], v[20:21], v[20:21]
	v_add_f32_e32 v30, v31, v30
	v_add_f32_e32 v24, v25, v24
	v_add_f32_e32 v24, v24, v30
	v_add_f32_e32 v24, v27, v24
	v_add_f32_e32 v24, v26, v24
	ds_bpermute_b32 v25, v16, v24
	s_waitcnt lgkmcnt(0)
	v_add_f32_e32 v24, v24, v25
	ds_bpermute_b32 v25, v17, v24
	s_waitcnt lgkmcnt(0)
	v_add_f32_e32 v24, v24, v25
	ds_bpermute_b32 v25, v18, v24
	s_waitcnt lgkmcnt(0)
	v_add_f32_e32 v24, v24, v25
	ds_bpermute_b32 v25, v19, v24
	s_waitcnt lgkmcnt(0)
	v_add_f32_e32 v24, v24, v25
	v_fmamk_f32 v24, v24, 0x3c000000, v193
	v_cmp_gt_f32_e32 vcc, s67, v24
	v_mul_f32_e32 v25, 0x4f800000, v24
	s_nop 0
	v_cndmask_b32_e32 v24, v24, v25, vcc
	v_sqrt_f32_e32 v25, v24
	s_nop 0
	v_add_u32_e32 v26, -1, v25
	v_fma_f32 v27, -v26, v25, v24
	v_cmp_ge_f32_e64 s[2:3], 0, v27
	v_add_u32_e32 v27, 1, v25
	s_nop 0
	v_cndmask_b32_e64 v26, v25, v26, s[2:3]
	v_fma_f32 v25, -v27, v25, v24
	v_cmp_lt_f32_e64 s[2:3], 0, v25
	s_nop 1
	v_cndmask_b32_e64 v25, v26, v27, s[2:3]
	v_mul_f32_e32 v26, 0x37800000, v25
	v_cndmask_b32_e32 v25, v25, v26, vcc
	v_cmp_class_f32_e32 vcc, v24, v195
	s_nop 1
	v_cndmask_b32_e32 v24, v25, v24, vcc
	v_div_scale_f32 v25, s[2:3], v24, v24, 1.0
	v_rcp_f32_e32 v26, v25
	s_nop 0
	v_fma_f32 v27, -v25, v26, 1.0
	v_fmac_f32_e32 v26, v27, v26
	v_div_scale_f32 v27, vcc, 1.0, v24, 1.0
	v_mul_f32_e32 v30, v27, v26
	v_fma_f32 v31, -v25, v30, v27
	v_fmac_f32_e32 v30, v31, v26
	v_fma_f32 v25, -v25, v30, v27
	v_div_fmas_f32 v25, v25, v26, v30
	v_div_fixup_f32 v24, v25, v24, 1.0
	v_mul_f32_e32 v24, 0x3f24fd5c, v24
	v_pk_mul_f32 v[20:21], v[20:21], v[24:25] op_sel_hi:[1,0]
	v_pk_mul_f32 v[26:27], v[28:29], v[24:25] op_sel_hi:[1,0]
	v_pk_mul_f32 v[22:23], v[22:23], v[24:25] op_sel_hi:[1,0]
	v_pk_mul_f32 v[14:15], v[14:15], v[24:25] op_sel_hi:[1,0]
	v_pk_mul_f32 v[20:21], v[0:1], v[20:21]
	v_pk_mul_f32 v[26:27], v[2:3], v[26:27]
	v_pk_mul_f32 v[22:23], v[4:5], v[22:23]
	v_pk_mul_f32 v[14:15], v[6:7], v[14:15]
	v_cvt_pk_bf16_f32 v20, v20, v21
	v_cvt_pk_bf16_f32 v21, v26, v27
	v_cvt_pk_bf16_f32 v22, v22, v23
	v_cvt_pk_bf16_f32 v23, v14, v15
	global_store_dwordx4 v[10:11], v[20:23], off
	v_lshl_add_u64 v[10:11], v[10:11], 0, s[10:11]
	s_cbranch_scc0 .LBB0_28
